# adds: attention waves 4-7 staggered by s_sleep 4 after each unit's K/V staging barrier (same-program wave stagger)
# baseline (speedup 1.0000x reference)
; #define LAS __attribute__((address_space(3)))
; __device__ __forceinline__ void attn_phase(LAS unsigned char* lds, const bf16_t* Q, const bf16_t* Kb, const bf16_t* Vt, bf16_t* AO, const float* sink, const float* qg, const float* kg) {
;     ...
;         const int kvh = uid & 3, nb = (uid >> 2) & 31, b = uid >> 7;
;         __syncthreads();
; #pragma unroll
;         for (int it = 0; it < 6; ++it) { const int idx = it * NTHR + tid, row = idx >> 3, ch = idx & 7; *(LAS u32x4*)(Kl + row * KROW + ch * 16) = kreg[it]; }
; #pragma unroll
;         for (int it = 0; it < 6; ++it) { const int idx = it * NTHR + tid, d = idx / 48, ch = idx % 48; LAS u32x2* pp = (LAS u32x2*)(Vl + d * VROW + ch * 16); pp[0] = (u32x2){vreg[it].x, vreg[it].y}; pp[1] = (u32x2){vreg[it].z, vreg[it].w}; }
;         __syncthreads();
;         if (uid + G < 1024) ATT_LOAD(uid + G);
.LBB0_147:
	v_readlane_b32 s0, v255, 39
	s_add_i32 s41, s6, s0
	s_cmpk_gt_i32 s41, 0x3ff
	s_cselect_b64 s[28:29], -1, 0
	s_and_b64 vcc, exec, s[28:29]
	s_barrier
	s_waitcnt vmcnt(0)
	ds_write_b128 v247, v[116:119]
	ds_write_b128 v248, v[112:115]
	ds_write_b128 v249, v[120:123]
	ds_write_b128 v250, v[124:127]
	ds_write_b128 v251, v[128:131]
	ds_write_b128 v233, v[132:135]
	ds_write2_b64 v237, v[136:137], v[138:139] offset1:1
	ds_write2_b64 v202, v[140:141], v[142:143] offset1:1
	ds_write2_b64 v203, v[144:145], v[146:147] offset1:1
	ds_write2_b64 v204, v[148:149], v[150:151] offset1:1
	ds_write2_b64 v205, v[152:153], v[154:155] offset1:1
	ds_write2_b64 v231, v[156:157], v[158:159] offset1:1
	s_waitcnt lgkmcnt(0)
	s_barrier
	v_readfirstlane_b32 s32, v232
	s_bitcmp1_b32 s32, 8
	s_cbranch_scc0 .Lattn_nostag
	s_sleep 4
.Lattn_nostag:
	v_readlane_b32 s1, v255, 40
	s_cbranch_vccnz .LBB0_173
	s_lshl_b32 s2, s41, 5
	s_and_b32 s14, s2, 0xf80
	s_lshl_b32 s2, s41, 6
	s_addk_i32 s14, 0xff80
	s_and_b32 s16, s2, 0xc0
	v_mov_b32_e32 v114, v1
	v_mov_b32_e32 v115, v1
	s_ashr_i32 s15, s41, 7
	s_lshl_b32 s26, s16, 1
	v_add_u32_e32 v0, s14, v199
	s_movk_i32 s0, 0x1000
	v_mov_b32_e32 v112, v1
	v_mov_b32_e32 v113, v1
	v_mov_b64_e32 v[118:119], v[114:115]
	s_lshl_b32 s17, s15, 12
	v_lshl_add_u64 v[4:5], v[196:197], 0, s[26:27]
	v_cmp_gt_u32_e32 vcc, s0, v0
	v_mov_b64_e32 v[116:117], v[112:113]
	s_and_saveexec_b64 s[2:3], vcc
	s_cbranch_execz .LBB0_150
	v_or_b32_e32 v2, s17, v0
	v_ashrrev_i32_e32 v3, 31, v2
	v_lshlrev_b64 v[2:3], 9, v[2:3]
	v_lshl_add_u64 v[2:3], v[4:5], 0, v[2:3]
	global_load_dwordx4 v[116:119], v[2:3], off
